# layer 0's in-proj weight conversion also deferred from step 1 to the idle last round of layer 0's first gate/up GEMM; step-1 converters do 5 trips
# baseline (speedup 1.0000x reference)
; __device__ __forceinline__ void convert_layer(PP P, int l, LAS unsigned char* lds, const Ids I) {
;     ...
;     for (int u = BID; u < 7 * 176 + 64; u += NB) {
;         const int mi = u / 176, uu = u - mi * 176;
;         if (mi == 0)      conv_tile4(P->in[I_F1G] + wl, 1024, 2816, (bf16_t*)(ws + WS_WGU1), 5, uu, T, I);
;         else if (mi == 1) conv_tile4(P->in[I_F1U] + wl, 1024, 2816, (bf16_t*)(ws + WS_WGU1), 6, uu, T, I);
;         else if (mi == 2) conv_tile4(P->in[I_F1D] + wl, 2816, 1024, (bf16_t*)(ws + WS_WD1), 0, uu, T, I);
;         else if (mi == 3) conv_tile4(P->in[I_WIN] + wl, 1024, 2816, (bf16_t*)(ws + WS_WIN), 4, uu, T, I);
;         else if (mi == 4) conv_tile4(P->in[I_F2G] + wl, 1024, 2816, (bf16_t*)(ws + WS_WGU2), 5, uu, T, I);
;         else if (mi == 5) conv_tile4(P->in[I_F2U] + wl, 1024, 2816, (bf16_t*)(ws + WS_WGU2), 6, uu, T, I);
;         else if (mi == 6) conv_tile4(P->in[I_F2D] + wl, 2816, 1024, (bf16_t*)(ws + WS_WD2), 0, uu, T, I);
;         else              conv_tile4(P->in[I_WOUT] + (size_t)l * 1024 * 1024, 1024, 1024, (bf16_t*)(ws + WS_WOUT), 0, uu, T, I);
;     }
; __global__ void __launch_bounds__(512) mega(Params Pval) {
;     ...
;             } else if (sub == 1 || sub == 10) {
;                 EpiSwiGLU E{(bf16_t*)(ws + WS_R1)}; run_gemm(lds, (const bf16_t*)(ws + WS_HB), (const bf16_t*)(ws + (sub == 1 ? WS_WGU1 : WS_WGU2)), MT, 2 * FF, 1024, E, I);
.Lcv_c3:
	s_cmpk_lt_u32 s93, 0xac
	s_cbranch_scc1 .LBB0_413
	s_mov_b64 s[28:29], s[12:13]
	s_add_i32 s22, s93, 0x164
	s_add_i32 s3, s93, 0xfffffd44
	s_movk_i32 s100, 0x54
	s_mov_b64 s[26:27], 0
	s_branch .LBB0_504

; __device__ __forceinline__ void convert_layer(PP P, int l, LAS unsigned char* lds, const Ids I) {
;     ...
;     for (int u = BID; u < 7 * 176 + 64; u += NB) {
;         const int mi = u / 176, uu = u - mi * 176;
;         if (mi == 0)      conv_tile4(P->in[I_F1G] + wl, 1024, 2816, (bf16_t*)(ws + WS_WGU1), 5, uu, T, I);
;         else if (mi == 1) conv_tile4(P->in[I_F1U] + wl, 1024, 2816, (bf16_t*)(ws + WS_WGU1), 6, uu, T, I);
;         else if (mi == 2) conv_tile4(P->in[I_F1D] + wl, 2816, 1024, (bf16_t*)(ws + WS_WD1), 0, uu, T, I);
;         else if (mi == 3) conv_tile4(P->in[I_WIN] + wl, 1024, 2816, (bf16_t*)(ws + WS_WIN), 4, uu, T, I);
;         else if (mi == 4) conv_tile4(P->in[I_F2G] + wl, 1024, 2816, (bf16_t*)(ws + WS_WGU2), 5, uu, T, I);
;         else if (mi == 5) conv_tile4(P->in[I_F2U] + wl, 1024, 2816, (bf16_t*)(ws + WS_WGU2), 6, uu, T, I);
;         else if (mi == 6) conv_tile4(P->in[I_F2D] + wl, 2816, 1024, (bf16_t*)(ws + WS_WD2), 0, uu, T, I);
;         else              conv_tile4(P->in[I_WOUT] + (size_t)l * 1024 * 1024, 1024, 1024, (bf16_t*)(ws + WS_WOUT), 0, uu, T, I);
;     }
.LBB0_503:
	s_add_i32 s22, s22, s100
	s_add_i32 s3, s3, s100
	s_cmp_eq_u32 s33, 3
	s_cbranch_scc0 .Lcv_nr
	s_sub_i32 s6, s22, 0x2c0
	s_cmp_lt_u32 s6, 0x160
	s_cbranch_scc0 .Lcv_nr
	s_add_i32 s22, s22, 0x160
	s_add_i32 s3, s3, 0x160
.Lcv_nr:
	s_movk_i32 s6, 0x4d0
	s_cmp_eq_u32 s33, 4
	s_cselect_b32 s6, 0x150, s6
	s_cmp_eq_u32 s33, 10
	s_cselect_b32 s6, 0x2c0, s6
	s_cmp_eq_u32 s33, 12
	s_cselect_b32 s6, 0x510, s6
	s_cmp_eq_u32 s33, 13
	s_cselect_b32 s6, 0x410, s6
	s_cmp_lt_i32 s22, s6
	s_waitcnt lgkmcnt(0)
	s_cbranch_scc0 .Lcv_exit

; __device__ __forceinline__ void convert_layer(PP P, int l, LAS unsigned char* lds, const Ids I) {
;     ...
;     for (int u = BID; u < 7 * 176 + 64; u += NB) {
;         const int mi = u / 176, uu = u - mi * 176;
;         if (mi == 0)      conv_tile4(P->in[I_F1G] + wl, 1024, 2816, (bf16_t*)(ws + WS_WGU1), 5, uu, T, I);
;         else if (mi == 1) conv_tile4(P->in[I_F1U] + wl, 1024, 2816, (bf16_t*)(ws + WS_WGU1), 6, uu, T, I);
;         else if (mi == 2) conv_tile4(P->in[I_F1D] + wl, 2816, 1024, (bf16_t*)(ws + WS_WD1), 0, uu, T, I);
;         else if (mi == 3) conv_tile4(P->in[I_WIN] + wl, 1024, 2816, (bf16_t*)(ws + WS_WIN), 4, uu, T, I);
;         else if (mi == 4) conv_tile4(P->in[I_F2G] + wl, 1024, 2816, (bf16_t*)(ws + WS_WGU2), 5, uu, T, I);
;         else if (mi == 5) conv_tile4(P->in[I_F2U] + wl, 1024, 2816, (bf16_t*)(ws + WS_WGU2), 6, uu, T, I);
;         else if (mi == 6) conv_tile4(P->in[I_F2D] + wl, 2816, 1024, (bf16_t*)(ws + WS_WD2), 0, uu, T, I);
;         else              conv_tile4(P->in[I_WOUT] + (size_t)l * 1024 * 1024, 1024, 1024, (bf16_t*)(ws + WS_WOUT), 0, uu, T, I);
;     }
.LBB0_658:
	s_add_i32 s16, s17, s16
	s_sub_i32 s18, s16, 0x420
	s_cmpk_lt_i32 s16, 0x210
	s_cbranch_scc1 .Lcv1_a
	s_add_i32 s18, s18, 0xb0
	s_cmpk_lt_i32 s16, 0x370
	s_cbranch_scc1 .Lcv1_a
	s_add_i32 s18, s18, 0xb0
.Lcv1_a:
	s_cmpk_gt_i32 s16, 0x397
	s_waitcnt lgkmcnt(0)
	s_cbranch_scc1 .LBB0_687

; __device__ __forceinline__ void convert_layer(PP P, int l, LAS unsigned char* lds, const Ids I) {
;     ...
;     for (int u = BID; u < 7 * 176 + 64; u += NB) {
;         const int mi = u / 176, uu = u - mi * 176;
;         if (mi == 0)      conv_tile4(P->in[I_F1G] + wl, 1024, 2816, (bf16_t*)(ws + WS_WGU1), 5, uu, T, I);
;         else if (mi == 1) conv_tile4(P->in[I_F1U] + wl, 1024, 2816, (bf16_t*)(ws + WS_WGU1), 6, uu, T, I);
;         else if (mi == 2) conv_tile4(P->in[I_F1D] + wl, 2816, 1024, (bf16_t*)(ws + WS_WD1), 0, uu, T, I);
;         else if (mi == 3) conv_tile4(P->in[I_WIN] + wl, 1024, 2816, (bf16_t*)(ws + WS_WIN), 4, uu, T, I);
;         else if (mi == 4) conv_tile4(P->in[I_F2G] + wl, 1024, 2816, (bf16_t*)(ws + WS_WGU2), 5, uu, T, I);
;         else if (mi == 5) conv_tile4(P->in[I_F2U] + wl, 1024, 2816, (bf16_t*)(ws + WS_WGU2), 6, uu, T, I);
;         else if (mi == 6) conv_tile4(P->in[I_F2D] + wl, 2816, 1024, (bf16_t*)(ws + WS_WD2), 0, uu, T, I);
;         else              conv_tile4(P->in[I_WOUT] + (size_t)l * 1024 * 1024, 1024, 1024, (bf16_t*)(ws + WS_WOUT), 0, uu, T, I);
;     }
; __global__ void __launch_bounds__(512) mega(Params Pval) {
;     ...
;             if (I.nb > 144) { if (I.bid < 72) { EpiAda E{(float*)(ws + WS_MOD), P->in[I_BADA]}; run_gemm(lds, (const bf16_t*)(ws + WS_AADA), (const bf16_t*)(ws + WS_R2), 256, 2 * 9216, 1024, E, I); }
;                               else { Ids J = I; J.bid = I.bid - 72; J.nb = I.nb - 72; convert_layer(P, 0, lds, J); } }
.LBB0_715:
	s_barrier
	s_cmp_gt_u32 s93, 23
	s_cbranch_scc1 .LBB0_716
	s_add_i32 s16, s93, 0x398
	s_movk_i32 s17, 0x1000
	s_add_i32 s18, s93, 0xd8
	s_add_u32 s48, s86, 0x4000
	s_addc_u32 s49, s87, 0
	s_branch .LBB0_659
